# PV section: V-fragment tr reads for next d-group rotated into the MFMA shadow (lag-1), MoBA loop + MoBA peeled + MLA loop
# baseline (speedup 1.0000x reference)
; __device__ __forceinline__ unsigned cvt_pk_bf16(float lo, float hi) { f32x2 v = {lo, hi}; bf16x2_t b = __builtin_convertvector(v, bf16x2_t); return __builtin_bit_cast(unsigned, b); }
; #define LAS __attribute__((address_space(3)))
; #define MFMA32(a, b, c) __builtin_amdgcn_mfma_f32_32x32x16_bf16((a), (b), (c), 0, 0, 0)
; template <int DQK, bool MOBA>
; __device__ __forceinline__ void attn_unit(const Args& A, int b, int h, int qb, lptr lds) {
;     ...
;             float ls = 0.f;
; #pragma unroll
;             for (int r = 0; r < 16; ++r) { s0[r] = __builtin_amdgcn_exp2f(s0[r]); s1[r] = __builtin_amdgcn_exp2f(s1[r]); ls += s0[r] + s1[r]; }
;             lrow += ls;
;             bf16x8 pb[4];
; #pragma unroll
;             for (int g = 0; g < 2; ++g) {
;                 u32x4 w0, w1;
;                 w0.x = cvt_pk_bf16(s0[8 * g + 0], s0[8 * g + 1]); w0.y = cvt_pk_bf16(s0[8 * g + 2], s0[8 * g + 3]); w0.z = cvt_pk_bf16(s0[8 * g + 4], s0[8 * g + 5]); w0.w = cvt_pk_bf16(s0[8 * g + 6], s0[8 * g + 7]);
;                 w1.x = cvt_pk_bf16(s1[8 * g + 0], s1[8 * g + 1]); w1.y = cvt_pk_bf16(s1[8 * g + 2], s1[8 * g + 3]); w1.z = cvt_pk_bf16(s1[8 * g + 4], s1[8 * g + 5]); w1.w = cvt_pk_bf16(s1[8 * g + 6], s1[8 * g + 7]);
;                 pb[g] = __builtin_bit_cast(bf16x8, w0); pb[2 + g] = __builtin_bit_cast(bf16x8, w1);
;             }
;             lptr vb = lds + L::OFF_V + buf * L::VBUF + (4 * hi + ((lane & 15) >> 2)) * VROW + ((lane >> 4) & 1) * 32 + (lane & 3) * 8;
; #pragma unroll
;             for (int d = 0; d < 4; ++d) {
;                 s16x4 lo[4], hi4[4];
; #pragma unroll
;                 for (int g = 0; g < 4; ++g) {
;                     lo[g] = __builtin_bit_cast(s16x4, __builtin_amdgcn_ds_read_tr16_b64_v4i16((LAS s16x4*)(vb + (16 * g) * VROW + d * 64)));
;                     hi4[g] = __builtin_bit_cast(s16x4, __builtin_amdgcn_ds_read_tr16_b64_v4i16((LAS s16x4*)(vb + (16 * g + 8) * VROW + d * 64)));
;                 }
;                 __builtin_amdgcn_sched_barrier(0);
; #pragma unroll
;                 for (int g = 0; g < 4; ++g) {
;                     const bf16x8 av = __builtin_shufflevector(lo[g], hi4[g], 0, 1, 2, 3, 4, 5, 6, 7);
;                     o[d] = MFMA32(av, pb[g], o[d]);
;                 }
;             }
.Lmoba_hd_done_a:
	v_exp_f32_e32 v188, v106
	v_exp_f32_e32 v189, v110
	v_exp_f32_e32 v190, v107
	v_exp_f32_e32 v191, v111
	v_exp_f32_e32 v192, v104
	v_exp_f32_e32 v193, v108
	v_exp_f32_e32 v194, v105
	v_exp_f32_e32 v195, v109
	v_add_f32_e32 v106, v188, v189
	v_add_f32_e32 v106, 0, v106
	v_add_f32_e32 v107, v190, v191
	v_add_f32_e32 v106, v107, v106
	v_add_f32_e32 v104, v192, v193
	v_add_f32_e32 v104, v104, v106
	v_add_f32_e32 v105, v194, v195
	v_add_f32_e32 v108, v105, v104
	v_exp_f32_e32 v107, v98
	v_exp_f32_e32 v105, v102
	v_exp_f32_e32 v106, v99
	v_exp_f32_e32 v104, v103
	v_exp_f32_e32 v103, v100
	v_exp_f32_e32 v102, v101
	v_exp_f32_e32 v109, v88
	v_pk_add_f32 v[98:99], v[106:107], v[104:105]
	v_exp_f32_e32 v111, v80
	v_add_f32_e32 v99, v99, v108
	v_add_f32_e32 v108, v98, v99
	v_exp_f32_e32 v99, v94
	v_exp_f32_e32 v98, v97
	v_exp_f32_e32 v97, v92
	v_exp_f32_e32 v110, v81
	v_exp_f32_e32 v187, v86
	v_pk_add_f32 v[100:101], v[98:99], v[102:103]
	v_exp_f32_e32 v186, v87
	v_add_f32_e32 v94, v101, v108
	v_add_f32_e32 v108, v100, v94
	v_exp_f32_e32 v101, v96
	v_exp_f32_e32 v96, v91
	v_exp_f32_e32 v100, v95
	v_pk_mov_b32 v[86:87], v[104:105], v[104:105] op_sel:[1,0]
	s_mulk_i32 s24, 0x5000
	v_cvt_pk_bf16_f32 v86, v86, v87
	v_pk_add_f32 v[94:95], v[96:97], v[100:101]
	v_pk_add_f32 v[80:81], v[110:111], v[186:187]
	v_add_f32_e32 v91, v95, v108
	v_add_f32_e32 v92, v94, v91
	v_exp_f32_e32 v91, v84
	v_exp_f32_e32 v95, v90
	v_exp_f32_e32 v90, v85
	v_exp_f32_e32 v94, v93
	v_exp_f32_e32 v93, v82
	v_exp_f32_e32 v108, v89
	v_pk_mov_b32 v[88:89], v[102:103], v[102:103] op_sel:[1,0]
	v_pk_add_f32 v[84:85], v[90:91], v[94:95]
	v_cvt_pk_bf16_f32 v87, v88, v89
	v_add_f32_e32 v85, v85, v92
	v_exp_f32_e32 v92, v83
	v_pk_mov_b32 v[88:89], v[96:97], v[96:97] op_sel:[1,0]
	v_pk_mov_b32 v[90:91], v[90:91], v[90:91] op_sel:[1,0]
	v_add_f32_e32 v84, v84, v85
	v_pk_add_f32 v[82:83], v[92:93], v[108:109]
	v_cvt_pk_bf16_f32 v88, v88, v89
	v_cvt_pk_bf16_f32 v89, v90, v91
	v_pk_mov_b32 v[90:91], v[92:93], v[92:93] op_sel:[1,0]
	v_pk_mov_b32 v[92:93], v[110:111], v[110:111] op_sel:[1,0]
	v_add_f32_e32 v83, v83, v84
	v_cvt_pk_bf16_f32 v90, v90, v91
	v_cvt_pk_bf16_f32 v91, v92, v93
	v_pk_mov_b32 v[92:93], v[100:101], v[100:101] op_sel:[1,0]
	v_pk_mov_b32 v[94:95], v[94:95], v[94:95] op_sel:[1,0]
	v_add_f32_e32 v82, v82, v83
	v_cvt_pk_bf16_f32 v92, v92, v93
	v_cvt_pk_bf16_f32 v93, v94, v95
	v_pk_mov_b32 v[94:95], v[108:109], v[108:109] op_sel:[1,0]
	v_pk_mov_b32 v[96:97], v[186:187], v[186:187] op_sel:[1,0]
	v_add_u32_e32 v186, s24, v183
	v_add_f32_e32 v81, v81, v82
	v_pk_mov_b32 v[82:83], v[106:107], v[106:107] op_sel:[1,0]
	v_pk_mov_b32 v[84:85], v[98:99], v[98:99] op_sel:[1,0]
	v_cvt_pk_bf16_f32 v94, v94, v95
	v_cvt_pk_bf16_f32 v95, v96, v97
	ds_read_b64_tr_b16 v[96:97], v186 offset:34816
	ds_read_b64_tr_b16 v[98:99], v186 offset:37376
	ds_read_b64_tr_b16 v[100:101], v186 offset:39936
	ds_read_b64_tr_b16 v[102:103], v186 offset:42496
	ds_read_b64_tr_b16 v[104:105], v186 offset:45056
	ds_read_b64_tr_b16 v[106:107], v186 offset:47616
	ds_read_b64_tr_b16 v[108:109], v186 offset:50176
	ds_read_b64_tr_b16 v[110:111], v186 offset:52736
	v_add_f32_e32 v196, v80, v81
	v_cvt_pk_bf16_f32 v80, v188, v190
	v_cvt_pk_bf16_f32 v81, v192, v194
	v_cvt_pk_bf16_f32 v82, v82, v83
	v_cvt_pk_bf16_f32 v83, v84, v85
	v_cvt_pk_bf16_f32 v84, v189, v191
	v_cvt_pk_bf16_f32 v85, v193, v195
	s_waitcnt lgkmcnt(6)
	v_mfma_f32_32x32x16_bf16 v[48:63], v[96:99], v[80:83], v[48:63]
	s_waitcnt lgkmcnt(4)
	v_mfma_f32_32x32x16_bf16 v[48:63], v[100:103], v[88:91], v[48:63]
	ds_read_b64_tr_b16 v[96:97], v186 offset:34880
	ds_read_b64_tr_b16 v[98:99], v186 offset:37440
	s_waitcnt lgkmcnt(4)
	v_mfma_f32_32x32x16_bf16 v[48:63], v[104:107], v[84:87], v[48:63]
	ds_read_b64_tr_b16 v[100:101], v186 offset:40000
	ds_read_b64_tr_b16 v[102:103], v186 offset:42560
	s_waitcnt lgkmcnt(4)
	v_mfma_f32_32x32x16_bf16 v[48:63], v[108:111], v[92:95], v[48:63]
	ds_read_b64_tr_b16 v[104:105], v186 offset:45120
	ds_read_b64_tr_b16 v[106:107], v186 offset:47680
	ds_read_b64_tr_b16 v[108:109], v186 offset:50240
	ds_read_b64_tr_b16 v[110:111], v186 offset:52800
	s_waitcnt lgkmcnt(6)
	v_mfma_f32_32x32x16_bf16 v[32:47], v[96:99], v[80:83], v[32:47]
	s_waitcnt lgkmcnt(4)
	v_mfma_f32_32x32x16_bf16 v[32:47], v[100:103], v[88:91], v[32:47]
	ds_read_b64_tr_b16 v[96:97], v186 offset:34944
	ds_read_b64_tr_b16 v[98:99], v186 offset:37504
	s_waitcnt lgkmcnt(4)
	v_mfma_f32_32x32x16_bf16 v[32:47], v[104:107], v[84:87], v[32:47]
	ds_read_b64_tr_b16 v[100:101], v186 offset:40064
	ds_read_b64_tr_b16 v[102:103], v186 offset:42624
	s_waitcnt lgkmcnt(4)
	v_mfma_f32_32x32x16_bf16 v[32:47], v[108:111], v[92:95], v[32:47]
	ds_read_b64_tr_b16 v[104:105], v186 offset:45184
	ds_read_b64_tr_b16 v[106:107], v186 offset:47744
	ds_read_b64_tr_b16 v[108:109], v186 offset:50304
	ds_read_b64_tr_b16 v[110:111], v186 offset:52864
	s_waitcnt lgkmcnt(6)
	v_mfma_f32_32x32x16_bf16 v[16:31], v[96:99], v[80:83], v[16:31]
	s_waitcnt lgkmcnt(4)
	v_mfma_f32_32x32x16_bf16 v[16:31], v[100:103], v[88:91], v[16:31]
	ds_read_b64_tr_b16 v[96:97], v186 offset:35008
	ds_read_b64_tr_b16 v[98:99], v186 offset:37568
	s_waitcnt lgkmcnt(4)
	v_mfma_f32_32x32x16_bf16 v[16:31], v[104:107], v[84:87], v[16:31]
	ds_read_b64_tr_b16 v[100:101], v186 offset:40128
	ds_read_b64_tr_b16 v[102:103], v186 offset:42688
	s_waitcnt lgkmcnt(4)
	v_mfma_f32_32x32x16_bf16 v[16:31], v[108:111], v[92:95], v[16:31]
	ds_read_b64_tr_b16 v[104:105], v186 offset:45248
	ds_read_b64_tr_b16 v[106:107], v186 offset:47808
	ds_read_b64_tr_b16 v[108:109], v186 offset:50368
	ds_read_b64_tr_b16 v[110:111], v186 offset:52928
	s_waitcnt lgkmcnt(6)
	v_mfma_f32_32x32x16_bf16 v[0:15], v[96:99], v[80:83], v[0:15]
	v_add_f32_e32 v184, v184, v196
	s_waitcnt lgkmcnt(4)
	v_mfma_f32_32x32x16_bf16 v[0:15], v[100:103], v[88:91], v[0:15]
	s_waitcnt lgkmcnt(2)
	v_mfma_f32_32x32x16_bf16 v[0:15], v[104:107], v[84:87], v[0:15]
	s_waitcnt lgkmcnt(0)
	v_mfma_f32_32x32x16_bf16 v[0:15], v[108:111], v[92:95], v[0:15]

; __device__ __forceinline__ unsigned cvt_pk_bf16(float lo, float hi) { f32x2 v = {lo, hi}; bf16x2_t b = __builtin_convertvector(v, bf16x2_t); return __builtin_bit_cast(unsigned, b); }
; #define LAS __attribute__((address_space(3)))
; #define MFMA32(a, b, c) __builtin_amdgcn_mfma_f32_32x32x16_bf16((a), (b), (c), 0, 0, 0)
; template <int DQK, bool MOBA>
; __device__ __forceinline__ void attn_unit(const Args& A, int b, int h, int qb, lptr lds) {
;     ...
;             float ls = 0.f;
; #pragma unroll
;             for (int r = 0; r < 16; ++r) { s0[r] = __builtin_amdgcn_exp2f(s0[r]); s1[r] = __builtin_amdgcn_exp2f(s1[r]); ls += s0[r] + s1[r]; }
;             lrow += ls;
;             bf16x8 pb[4];
; #pragma unroll
;             for (int g = 0; g < 2; ++g) {
;                 u32x4 w0, w1;
;                 w0.x = cvt_pk_bf16(s0[8 * g + 0], s0[8 * g + 1]); w0.y = cvt_pk_bf16(s0[8 * g + 2], s0[8 * g + 3]); w0.z = cvt_pk_bf16(s0[8 * g + 4], s0[8 * g + 5]); w0.w = cvt_pk_bf16(s0[8 * g + 6], s0[8 * g + 7]);
;                 w1.x = cvt_pk_bf16(s1[8 * g + 0], s1[8 * g + 1]); w1.y = cvt_pk_bf16(s1[8 * g + 2], s1[8 * g + 3]); w1.z = cvt_pk_bf16(s1[8 * g + 4], s1[8 * g + 5]); w1.w = cvt_pk_bf16(s1[8 * g + 6], s1[8 * g + 7]);
;                 pb[g] = __builtin_bit_cast(bf16x8, w0); pb[2 + g] = __builtin_bit_cast(bf16x8, w1);
;             }
;             lptr vb = lds + L::OFF_V + buf * L::VBUF + (4 * hi + ((lane & 15) >> 2)) * VROW + ((lane >> 4) & 1) * 32 + (lane & 3) * 8;
; #pragma unroll
;             for (int d = 0; d < 4; ++d) {
;                 s16x4 lo[4], hi4[4];
; #pragma unroll
;                 for (int g = 0; g < 4; ++g) {
;                     lo[g] = __builtin_bit_cast(s16x4, __builtin_amdgcn_ds_read_tr16_b64_v4i16((LAS s16x4*)(vb + (16 * g) * VROW + d * 64)));
;                     hi4[g] = __builtin_bit_cast(s16x4, __builtin_amdgcn_ds_read_tr16_b64_v4i16((LAS s16x4*)(vb + (16 * g + 8) * VROW + d * 64)));
;                 }
;                 __builtin_amdgcn_sched_barrier(0);
; #pragma unroll
;                 for (int g = 0; g < 4; ++g) {
;                     const bf16x8 av = __builtin_shufflevector(lo[g], hi4[g], 0, 1, 2, 3, 4, 5, 6, 7);
;                     o[d] = MFMA32(av, pb[g], o[d]);
;                 }
;             }
.LBB0_802:
	s_nop 7
	v_exp_f32_e32 v98, v80
	s_nop 0
	v_exp_f32_e32 v99, v64
	v_exp_f32_e32 v100, v81
	v_exp_f32_e32 v101, v65
	v_exp_f32_e32 v102, v82
	v_exp_f32_e32 v103, v66
	v_exp_f32_e32 v104, v83
	v_exp_f32_e32 v105, v67
	v_add_f32_e32 v64, v98, v99
	v_exp_f32_e32 v67, v84
	v_exp_f32_e32 v81, v68
	v_exp_f32_e32 v66, v85
	v_exp_f32_e32 v80, v69
	v_add_f32_e32 v64, 0, v64
	v_add_f32_e32 v65, v100, v101
	v_add_f32_e32 v64, v65, v64
	v_add_f32_e32 v65, v102, v103
	v_add_f32_e32 v64, v65, v64
	v_add_f32_e32 v65, v104, v105
	v_add_f32_e32 v82, v65, v64
	v_pk_add_f32 v[64:65], v[66:67], v[80:81]
	v_exp_f32_e32 v69, v86
	v_add_f32_e32 v65, v65, v82
	v_exp_f32_e32 v83, v70
	v_exp_f32_e32 v68, v87
	v_exp_f32_e32 v82, v71
	v_add_f32_e32 v84, v64, v65
	v_exp_f32_e32 v85, v88
	v_exp_f32_e32 v87, v72
	v_pk_add_f32 v[64:65], v[68:69], v[82:83]
	v_exp_f32_e32 v86, v73
	v_add_f32_e32 v65, v65, v84
	v_exp_f32_e32 v84, v89
	v_exp_f32_e32 v89, v90
	v_exp_f32_e32 v97, v74
	v_exp_f32_e32 v88, v91
	v_exp_f32_e32 v96, v75
	v_add_f32_e32 v70, v64, v65
	v_pk_add_f32 v[64:65], v[84:85], v[86:87]
	v_exp_f32_e32 v75, v92
	v_exp_f32_e32 v91, v76
	v_exp_f32_e32 v74, v93
	v_exp_f32_e32 v90, v77
	v_add_f32_e32 v65, v65, v70
	v_add_f32_e32 v70, v64, v65
	v_pk_add_f32 v[64:65], v[88:89], v[96:97]
	v_exp_f32_e32 v77, v94
	v_exp_f32_e32 v93, v78
	v_exp_f32_e32 v76, v95
	v_exp_f32_e32 v92, v79
	v_add_f32_e32 v65, v65, v70
	v_add_f32_e32 v70, v64, v65
	v_pk_add_f32 v[64:65], v[74:75], v[90:91]
	v_pk_mov_b32 v[72:73], v[82:83], v[82:83] op_sel:[1,0]
	v_add_f32_e32 v65, v65, v70
	v_add_f32_e32 v70, v64, v65
	v_pk_add_f32 v[64:65], v[76:77], v[92:93]
	v_pk_mov_b32 v[78:79], v[88:89], v[88:89] op_sel:[1,0]
	v_add_f32_e32 v65, v65, v70
	v_pk_mov_b32 v[70:71], v[80:81], v[80:81] op_sel:[1,0]
	v_pk_mov_b32 v[74:75], v[74:75], v[74:75] op_sel:[1,0]
	v_cvt_pk_bf16_f32 v70, v70, v71
	v_cvt_pk_bf16_f32 v71, v72, v73
	v_pk_mov_b32 v[72:73], v[84:85], v[84:85] op_sel:[1,0]
	v_pk_mov_b32 v[76:77], v[76:77], v[76:77] op_sel:[1,0]
	v_cvt_pk_bf16_f32 v72, v72, v73
	v_cvt_pk_bf16_f32 v73, v78, v79
	v_cvt_pk_bf16_f32 v74, v74, v75
	v_cvt_pk_bf16_f32 v75, v76, v77
	v_pk_mov_b32 v[76:77], v[86:87], v[86:87] op_sel:[1,0]
	v_pk_mov_b32 v[78:79], v[96:97], v[96:97] op_sel:[1,0]
	s_mulk_i32 s4, 0x5000
	v_cvt_pk_bf16_f32 v76, v76, v77
	v_cvt_pk_bf16_f32 v77, v78, v79
	v_pk_mov_b32 v[78:79], v[90:91], v[90:91] op_sel:[1,0]
	v_pk_mov_b32 v[80:81], v[92:93], v[92:93] op_sel:[1,0]
	v_add_u32_e32 v96, s4, v198
	v_cvt_pk_bf16_f32 v78, v78, v79
	v_cvt_pk_bf16_f32 v79, v80, v81
	v_add_u32_e32 v97, 0xc800, v96
	ds_read_b64_tr_b16 v[80:81], v96 offset:51200
	ds_read_b64_tr_b16 v[82:83], v96 offset:53760
	ds_read_b64_tr_b16 v[84:85], v96 offset:56320
	ds_read_b64_tr_b16 v[86:87], v96 offset:58880
	ds_read_b64_tr_b16 v[88:89], v96 offset:61440
	ds_read_b64_tr_b16 v[90:91], v96 offset:64000
	ds_read_b64_tr_b16 v[92:93], v97 offset:15360
	ds_read_b64_tr_b16 v[94:95], v97 offset:17920
	v_pk_mov_b32 v[66:67], v[66:67], v[66:67] op_sel:[1,0]
	v_pk_mov_b32 v[68:69], v[68:69], v[68:69] op_sel:[1,0]
	v_add_f32_e32 v106, v64, v65
	v_cvt_pk_bf16_f32 v64, v98, v100
	v_cvt_pk_bf16_f32 v65, v102, v104
	v_cvt_pk_bf16_f32 v66, v66, v67
	v_cvt_pk_bf16_f32 v67, v68, v69
	v_cvt_pk_bf16_f32 v68, v99, v101
	v_cvt_pk_bf16_f32 v69, v103, v105
	s_waitcnt lgkmcnt(6)
	v_mfma_f32_32x32x16_bf16 v[48:63], v[80:83], v[64:67], v[48:63]
	s_waitcnt lgkmcnt(4)
	v_mfma_f32_32x32x16_bf16 v[48:63], v[84:87], v[72:75], v[48:63]
	ds_read_b64_tr_b16 v[80:81], v96 offset:51264
	ds_read_b64_tr_b16 v[82:83], v96 offset:53824
	s_waitcnt lgkmcnt(4)
	v_mfma_f32_32x32x16_bf16 v[48:63], v[88:91], v[68:71], v[48:63]
	ds_read_b64_tr_b16 v[84:85], v96 offset:56384
	ds_read_b64_tr_b16 v[86:87], v96 offset:58944
	s_waitcnt lgkmcnt(4)
	v_mfma_f32_32x32x16_bf16 v[48:63], v[92:95], v[76:79], v[48:63]
	ds_read_b64_tr_b16 v[88:89], v96 offset:61504
	ds_read_b64_tr_b16 v[90:91], v96 offset:64064
	ds_read_b64_tr_b16 v[92:93], v97 offset:15424
	ds_read_b64_tr_b16 v[94:95], v97 offset:17984
	s_waitcnt lgkmcnt(6)
	v_mfma_f32_32x32x16_bf16 v[32:47], v[80:83], v[64:67], v[32:47]
	s_waitcnt lgkmcnt(4)
	v_mfma_f32_32x32x16_bf16 v[32:47], v[84:87], v[72:75], v[32:47]
	ds_read_b64_tr_b16 v[80:81], v96 offset:51328
	ds_read_b64_tr_b16 v[82:83], v96 offset:53888
	s_waitcnt lgkmcnt(4)
	v_mfma_f32_32x32x16_bf16 v[32:47], v[88:91], v[68:71], v[32:47]
	ds_read_b64_tr_b16 v[84:85], v96 offset:56448
	ds_read_b64_tr_b16 v[86:87], v96 offset:59008
	s_waitcnt lgkmcnt(4)
	v_mfma_f32_32x32x16_bf16 v[32:47], v[92:95], v[76:79], v[32:47]
	ds_read_b64_tr_b16 v[88:89], v96 offset:61568
	ds_read_b64_tr_b16 v[90:91], v96 offset:64128
	ds_read_b64_tr_b16 v[92:93], v97 offset:15488
	ds_read_b64_tr_b16 v[94:95], v97 offset:18048
	s_waitcnt lgkmcnt(6)
	v_mfma_f32_32x32x16_bf16 v[16:31], v[80:83], v[64:67], v[16:31]
	s_waitcnt lgkmcnt(4)
	v_mfma_f32_32x32x16_bf16 v[16:31], v[84:87], v[72:75], v[16:31]
	ds_read_b64_tr_b16 v[80:81], v96 offset:51392
	ds_read_b64_tr_b16 v[82:83], v96 offset:53952
	s_waitcnt lgkmcnt(4)
	v_mfma_f32_32x32x16_bf16 v[16:31], v[88:91], v[68:71], v[16:31]
	ds_read_b64_tr_b16 v[84:85], v96 offset:56512
	ds_read_b64_tr_b16 v[86:87], v96 offset:59072
	s_waitcnt lgkmcnt(4)
	v_mfma_f32_32x32x16_bf16 v[16:31], v[92:95], v[76:79], v[16:31]
	ds_read_b64_tr_b16 v[88:89], v96 offset:61632
	ds_read_b64_tr_b16 v[90:91], v96 offset:64192
	ds_read_b64_tr_b16 v[92:93], v97 offset:15552
	ds_read_b64_tr_b16 v[94:95], v97 offset:18112
	s_waitcnt lgkmcnt(6)
	v_mfma_f32_32x32x16_bf16 v[0:15], v[80:83], v[64:67], v[0:15]
	v_add_f32_e32 v187, v187, v106
	s_waitcnt lgkmcnt(4)
	v_mfma_f32_32x32x16_bf16 v[0:15], v[84:87], v[72:75], v[0:15]
	s_waitcnt lgkmcnt(2)
	v_mfma_f32_32x32x16_bf16 v[0:15], v[88:91], v[68:71], v[0:15]
	s_waitcnt lgkmcnt(0)
	v_mfma_f32_32x32x16_bf16 v[0:15], v[92:95], v[76:79], v[0:15]

; __device__ __forceinline__ unsigned cvt_pk_bf16(float lo, float hi) { f32x2 v = {lo, hi}; bf16x2_t b = __builtin_convertvector(v, bf16x2_t); return __builtin_bit_cast(unsigned, b); }
; #define LAS __attribute__((address_space(3)))
; #define MFMA32(a, b, c) __builtin_amdgcn_mfma_f32_32x32x16_bf16((a), (b), (c), 0, 0, 0)
; template <int DQK, bool MOBA>
; __device__ __forceinline__ void attn_unit(const Args& A, int b, int h, int qb, lptr lds) {
;     ...
;             float ls = 0.f;
; #pragma unroll
;             for (int r = 0; r < 16; ++r) { s0[r] = __builtin_amdgcn_exp2f(s0[r]); s1[r] = __builtin_amdgcn_exp2f(s1[r]); ls += s0[r] + s1[r]; }
;             lrow += ls;
;             bf16x8 pb[4];
; #pragma unroll
;             for (int g = 0; g < 2; ++g) {
;                 u32x4 w0, w1;
;                 w0.x = cvt_pk_bf16(s0[8 * g + 0], s0[8 * g + 1]); w0.y = cvt_pk_bf16(s0[8 * g + 2], s0[8 * g + 3]); w0.z = cvt_pk_bf16(s0[8 * g + 4], s0[8 * g + 5]); w0.w = cvt_pk_bf16(s0[8 * g + 6], s0[8 * g + 7]);
;                 w1.x = cvt_pk_bf16(s1[8 * g + 0], s1[8 * g + 1]); w1.y = cvt_pk_bf16(s1[8 * g + 2], s1[8 * g + 3]); w1.z = cvt_pk_bf16(s1[8 * g + 4], s1[8 * g + 5]); w1.w = cvt_pk_bf16(s1[8 * g + 6], s1[8 * g + 7]);
;                 pb[g] = __builtin_bit_cast(bf16x8, w0); pb[2 + g] = __builtin_bit_cast(bf16x8, w1);
;             }
;             lptr vb = lds + L::OFF_V + buf * L::VBUF + (4 * hi + ((lane & 15) >> 2)) * VROW + ((lane >> 4) & 1) * 32 + (lane & 3) * 8;
; #pragma unroll
;             for (int d = 0; d < 4; ++d) {
;                 s16x4 lo[4], hi4[4];
; #pragma unroll
;                 for (int g = 0; g < 4; ++g) {
;                     lo[g] = __builtin_bit_cast(s16x4, __builtin_amdgcn_ds_read_tr16_b64_v4i16((LAS s16x4*)(vb + (16 * g) * VROW + d * 64)));
;                     hi4[g] = __builtin_bit_cast(s16x4, __builtin_amdgcn_ds_read_tr16_b64_v4i16((LAS s16x4*)(vb + (16 * g + 8) * VROW + d * 64)));
;                 }
;                 __builtin_amdgcn_sched_barrier(0);
; #pragma unroll
;                 for (int g = 0; g < 4; ++g) {
;                     const bf16x8 av = __builtin_shufflevector(lo[g], hi4[g], 0, 1, 2, 3, 4, 5, 6, 7);
;                     o[d] = MFMA32(av, pb[g], o[d]);
;                 }
;             }
.Lmla_hd_done_a:
	s_nop 7
	v_exp_f32_e32 v189, v96
	s_nop 0
	v_exp_f32_e32 v203, v80
	v_exp_f32_e32 v216, v97
	v_exp_f32_e32 v217, v81
	v_exp_f32_e32 v218, v98
	v_exp_f32_e32 v219, v82
	v_exp_f32_e32 v220, v99
	v_exp_f32_e32 v221, v83
	v_add_f32_e32 v80, v189, v203
	v_exp_f32_e32 v83, v100
	v_exp_f32_e32 v97, v84
	v_exp_f32_e32 v82, v101
	v_exp_f32_e32 v96, v85
	v_add_f32_e32 v80, 0, v80
	v_add_f32_e32 v81, v216, v217
	v_add_f32_e32 v80, v81, v80
	v_add_f32_e32 v81, v218, v219
	v_add_f32_e32 v80, v81, v80
	v_add_f32_e32 v81, v220, v221
	v_add_f32_e32 v98, v81, v80
	v_pk_add_f32 v[80:81], v[82:83], v[96:97]
	v_exp_f32_e32 v85, v102
	v_add_f32_e32 v81, v81, v98
	v_exp_f32_e32 v99, v86
	v_exp_f32_e32 v84, v103
	v_exp_f32_e32 v98, v87
	v_add_f32_e32 v100, v80, v81
	v_exp_f32_e32 v101, v104
	v_exp_f32_e32 v103, v88
	v_pk_add_f32 v[80:81], v[84:85], v[98:99]
	v_exp_f32_e32 v102, v89
	v_add_f32_e32 v81, v81, v100
	v_exp_f32_e32 v100, v105
	v_exp_f32_e32 v105, v106
	v_exp_f32_e32 v215, v90
	v_exp_f32_e32 v104, v107
	v_exp_f32_e32 v214, v91
	v_add_f32_e32 v86, v80, v81
	v_pk_add_f32 v[80:81], v[100:101], v[102:103]
	v_exp_f32_e32 v91, v108
	v_exp_f32_e32 v107, v92
	v_exp_f32_e32 v90, v109
	v_exp_f32_e32 v106, v93
	v_add_f32_e32 v81, v81, v86
	v_add_f32_e32 v86, v80, v81
	v_pk_add_f32 v[80:81], v[104:105], v[214:215]
	v_exp_f32_e32 v93, v110
	v_exp_f32_e32 v109, v94
	v_exp_f32_e32 v92, v111
	v_exp_f32_e32 v108, v95
	v_add_f32_e32 v81, v81, v86
	v_add_f32_e32 v86, v80, v81
	v_pk_add_f32 v[80:81], v[90:91], v[106:107]
	v_pk_mov_b32 v[88:89], v[98:99], v[98:99] op_sel:[1,0]
	v_add_f32_e32 v81, v81, v86
	v_add_f32_e32 v86, v80, v81
	v_pk_add_f32 v[80:81], v[92:93], v[108:109]
	v_pk_mov_b32 v[94:95], v[104:105], v[104:105] op_sel:[1,0]
	v_add_f32_e32 v81, v81, v86
	v_pk_mov_b32 v[86:87], v[96:97], v[96:97] op_sel:[1,0]
	v_pk_mov_b32 v[90:91], v[90:91], v[90:91] op_sel:[1,0]
	v_cvt_pk_bf16_f32 v86, v86, v87
	v_cvt_pk_bf16_f32 v87, v88, v89
	v_pk_mov_b32 v[88:89], v[100:101], v[100:101] op_sel:[1,0]
	v_pk_mov_b32 v[92:93], v[92:93], v[92:93] op_sel:[1,0]
	v_cvt_pk_bf16_f32 v88, v88, v89
	v_cvt_pk_bf16_f32 v89, v94, v95
	v_cvt_pk_bf16_f32 v90, v90, v91
	v_cvt_pk_bf16_f32 v91, v92, v93
	v_pk_mov_b32 v[92:93], v[102:103], v[102:103] op_sel:[1,0]
	v_pk_mov_b32 v[94:95], v[214:215], v[214:215] op_sel:[1,0]
	s_mulk_i32 s44, 0x5000
	v_add_f32_e32 v222, v80, v81
	v_cvt_pk_bf16_f32 v80, v189, v216
	v_pk_mov_b32 v[82:83], v[82:83], v[82:83] op_sel:[1,0]
	v_pk_mov_b32 v[84:85], v[84:85], v[84:85] op_sel:[1,0]
	v_cvt_pk_bf16_f32 v92, v92, v93
	v_cvt_pk_bf16_f32 v93, v94, v95
	v_pk_mov_b32 v[94:95], v[106:107], v[106:107] op_sel:[1,0]
	v_pk_mov_b32 v[96:97], v[108:109], v[108:109] op_sel:[1,0]
	v_add_u32_e32 v189, s44, v198
	v_cvt_pk_bf16_f32 v82, v82, v83
	v_cvt_pk_bf16_f32 v83, v84, v85
	v_cvt_pk_bf16_f32 v84, v203, v217
	v_cvt_pk_bf16_f32 v94, v94, v95
	v_cvt_pk_bf16_f32 v95, v96, v97
	v_add_u32_e32 v203, 0xc800, v189
	ds_read_b64_tr_b16 v[96:97], v189 offset:51200
	ds_read_b64_tr_b16 v[98:99], v189 offset:53760
	ds_read_b64_tr_b16 v[100:101], v189 offset:56320
	ds_read_b64_tr_b16 v[102:103], v189 offset:58880
	ds_read_b64_tr_b16 v[104:105], v189 offset:61440
	ds_read_b64_tr_b16 v[106:107], v189 offset:64000
	ds_read_b64_tr_b16 v[108:109], v203 offset:15360
	ds_read_b64_tr_b16 v[110:111], v203 offset:17920
	v_cvt_pk_bf16_f32 v81, v218, v220
	v_cvt_pk_bf16_f32 v85, v219, v221
	s_waitcnt lgkmcnt(6)
	v_mfma_f32_32x32x16_bf16 v[48:63], v[96:99], v[80:83], v[48:63]
	s_waitcnt lgkmcnt(4)
	v_mfma_f32_32x32x16_bf16 v[48:63], v[100:103], v[88:91], v[48:63]
	ds_read_b64_tr_b16 v[96:97], v189 offset:51264
	ds_read_b64_tr_b16 v[98:99], v189 offset:53824
	s_waitcnt lgkmcnt(4)
	v_mfma_f32_32x32x16_bf16 v[48:63], v[104:107], v[84:87], v[48:63]
	ds_read_b64_tr_b16 v[100:101], v189 offset:56384
	ds_read_b64_tr_b16 v[102:103], v189 offset:58944
	s_waitcnt lgkmcnt(4)
	v_mfma_f32_32x32x16_bf16 v[48:63], v[108:111], v[92:95], v[48:63]
	ds_read_b64_tr_b16 v[104:105], v189 offset:61504
	ds_read_b64_tr_b16 v[106:107], v189 offset:64064
	ds_read_b64_tr_b16 v[108:109], v203 offset:15424
	ds_read_b64_tr_b16 v[110:111], v203 offset:17984
	s_waitcnt lgkmcnt(6)
	v_mfma_f32_32x32x16_bf16 v[32:47], v[96:99], v[80:83], v[32:47]
	s_waitcnt lgkmcnt(4)
	v_mfma_f32_32x32x16_bf16 v[32:47], v[100:103], v[88:91], v[32:47]
	ds_read_b64_tr_b16 v[96:97], v189 offset:51328
	ds_read_b64_tr_b16 v[98:99], v189 offset:53888
	s_waitcnt lgkmcnt(4)
	v_mfma_f32_32x32x16_bf16 v[32:47], v[104:107], v[84:87], v[32:47]
	ds_read_b64_tr_b16 v[100:101], v189 offset:56448
	ds_read_b64_tr_b16 v[102:103], v189 offset:59008
	s_waitcnt lgkmcnt(4)
	v_mfma_f32_32x32x16_bf16 v[32:47], v[108:111], v[92:95], v[32:47]
	ds_read_b64_tr_b16 v[104:105], v189 offset:61568
	ds_read_b64_tr_b16 v[106:107], v189 offset:64128
	ds_read_b64_tr_b16 v[108:109], v203 offset:15488
	ds_read_b64_tr_b16 v[110:111], v203 offset:18048
	s_waitcnt lgkmcnt(6)
	v_mfma_f32_32x32x16_bf16 v[16:31], v[96:99], v[80:83], v[16:31]
	s_waitcnt lgkmcnt(4)
	v_mfma_f32_32x32x16_bf16 v[16:31], v[100:103], v[88:91], v[16:31]
	ds_read_b64_tr_b16 v[96:97], v189 offset:51392
	ds_read_b64_tr_b16 v[98:99], v189 offset:53952
	s_waitcnt lgkmcnt(4)
	v_mfma_f32_32x32x16_bf16 v[16:31], v[104:107], v[84:87], v[16:31]
	ds_read_b64_tr_b16 v[100:101], v189 offset:56512
	ds_read_b64_tr_b16 v[102:103], v189 offset:59072
	s_waitcnt lgkmcnt(4)
	v_mfma_f32_32x32x16_bf16 v[16:31], v[108:111], v[92:95], v[16:31]
	ds_read_b64_tr_b16 v[104:105], v189 offset:61632
	ds_read_b64_tr_b16 v[106:107], v189 offset:64192
	ds_read_b64_tr_b16 v[108:109], v203 offset:15552
	ds_read_b64_tr_b16 v[110:111], v203 offset:18112
	s_waitcnt lgkmcnt(6)
	v_mfma_f32_32x32x16_bf16 v[0:15], v[96:99], v[80:83], v[0:15]
	v_add_f32_e32 v187, v187, v222
	s_waitcnt lgkmcnt(4)
	v_mfma_f32_32x32x16_bf16 v[0:15], v[100:103], v[88:91], v[0:15]
	s_waitcnt lgkmcnt(2)
	v_mfma_f32_32x32x16_bf16 v[0:15], v[104:107], v[84:87], v[0:15]
	s_waitcnt lgkmcnt(0)
	v_mfma_f32_32x32x16_bf16 v[0:15], v[108:111], v[92:95], v[0:15]
